# MoE weight conversion convert step: per-read lgkmcnt waits (7..0) instead of one lgkmcnt(0) after the eight LDS tile reads
# baseline (speedup 1.0000x reference)
.LBB0_805:
	s_waitcnt lgkmcnt(0)
	s_barrier
	s_waitcnt vmcnt(8)
	ds_read2st64_b64 v[12:15], v10 offset1:1
	ds_read2st64_b64 v[16:19], v10 offset0:2 offset1:3
	ds_read2st64_b64 v[20:23], v10 offset0:4 offset1:5
	ds_read2st64_b64 v[24:27], v10 offset0:6 offset1:7
	ds_read2st64_b64 v[28:31], v10 offset0:8 offset1:9
	ds_read2st64_b64 v[32:35], v10 offset0:10 offset1:11
	ds_read2st64_b64 v[36:39], v10 offset0:12 offset1:13
	ds_read2st64_b64 v[40:43], v10 offset0:14 offset1:15
	s_waitcnt lgkmcnt(7)
	v_mul_f32_e32 v44, 0x42000000, v12
	v_mul_f32_e32 v14, 0x42000000, v14
	v_mov_b32_e32 v12, 0
	v_cvt_pk_fp8_f32 v12, v44, v14
	v_mul_f32_e32 v14, 0x42000000, v13
	v_mul_f32_e32 v15, 0x42000000, v15
	v_mov_b32_e32 v13, 0
	v_cvt_pk_fp8_f32 v13, v14, v15
	s_waitcnt lgkmcnt(6)
	v_mul_f32_e32 v16, 0x42000000, v16
	v_mul_f32_e32 v18, 0x42000000, v18
	v_mul_f32_e32 v14, 0x42000000, v17
	v_mul_f32_e32 v15, 0x42000000, v19
	v_cvt_pk_fp8_f32 v12, v16, v18 op_sel:[0,0,1]
	v_cvt_pk_fp8_f32 v13, v14, v15 op_sel:[0,0,1]
	s_waitcnt lgkmcnt(5)
	v_mul_f32_e32 v15, 0x42000000, v20
	v_mul_f32_e32 v16, 0x42000000, v22
	v_mov_b32_e32 v14, 0
	v_cvt_pk_fp8_f32 v14, v15, v16
	v_mul_f32_e32 v16, 0x42000000, v21
	v_mul_f32_e32 v19, 0x42000000, v23
	v_mov_b32_e32 v15, 0
	v_cvt_pk_fp8_f32 v15, v16, v19
	s_waitcnt lgkmcnt(4)
	v_mul_f32_e32 v17, 0x42000000, v24
	v_mul_f32_e32 v18, 0x42000000, v26
	v_cvt_pk_fp8_f32 v14, v17, v18 op_sel:[0,0,1]
	v_mul_f32_e32 v16, 0x42000000, v25
	v_mul_f32_e32 v17, 0x42000000, v27
	v_cvt_pk_fp8_f32 v15, v16, v17 op_sel:[0,0,1]
	s_waitcnt lgkmcnt(3)
	v_mul_f32_e32 v17, 0x42000000, v28
	v_mul_f32_e32 v18, 0x42000000, v30
	v_mov_b32_e32 v16, 0
	v_cvt_pk_fp8_f32 v16, v17, v18
	v_mul_f32_e32 v18, 0x42000000, v29
	v_mul_f32_e32 v21, 0x42000000, v31
	v_mov_b32_e32 v17, 0
	v_cvt_pk_fp8_f32 v17, v18, v21
	s_waitcnt lgkmcnt(2)
	v_mul_f32_e32 v19, 0x42000000, v32
	v_mul_f32_e32 v20, 0x42000000, v34
	v_cvt_pk_fp8_f32 v16, v19, v20 op_sel:[0,0,1]
	v_mul_f32_e32 v18, 0x42000000, v33
	v_mul_f32_e32 v19, 0x42000000, v35
	v_cvt_pk_fp8_f32 v17, v18, v19 op_sel:[0,0,1]
	s_waitcnt lgkmcnt(1)
	v_mul_f32_e32 v19, 0x42000000, v36
	v_mul_f32_e32 v20, 0x42000000, v38
	v_mov_b32_e32 v18, 0
	v_cvt_pk_fp8_f32 v18, v19, v20
	v_mul_f32_e32 v20, 0x42000000, v37
	v_mul_f32_e32 v23, 0x42000000, v39
	v_mov_b32_e32 v19, 0
	v_cvt_pk_fp8_f32 v19, v20, v23
	s_waitcnt lgkmcnt(0)
	v_mul_f32_e32 v21, 0x42000000, v40
	v_mul_f32_e32 v22, 0x42000000, v42
	v_cvt_pk_fp8_f32 v18, v21, v22 op_sel:[0,0,1]
	v_mul_f32_e32 v20, 0x42000000, v41
	v_mul_f32_e32 v21, 0x42000000, v43
	v_cvt_pk_fp8_f32 v19, v20, v21 op_sel:[0,0,1]
	ds_write2st64_b64 v11, v[12:13], v[14:15] offset1:1
	ds_write2st64_b64 v11, v[16:17], v[18:19] offset0:2 offset1:3
	s_waitcnt lgkmcnt(0)
	s_add_i32 s37, s35, s2
	s_min_i32 s20, s37, s0
	s_cmpk_gt_i32 s20, 0x3fff
	s_mov_b64 s[18:19], -1
	s_cbranch_scc0 .LBB0_807
	s_add_i32 s4, s20, 0xffffc000
	s_lshr_b32 s16, s4, 8
	s_lshl_b64 s[4:5], s[16:17], 24
	s_add_u32 s4, s12, s4
	s_addc_u32 s5, s13, s5
	s_mov_b64 s[18:19], 0

.LBB0_814:
	s_lshl_b32 s20, s38, 3
	s_and_b32 s16, s20, s16
	s_lshl_b32 s20, s38, 7
	s_and_b32 s20, s20, 0x780
	s_add_u32 s18, s18, s20
	s_addc_u32 s19, s19, 0
	v_lshl_add_u64 v[24:25], s[18:19], 0, v[4:5]
	s_lshl_b32 s18, s16, 1
	s_ashr_i32 s19, s16, 4
	s_and_b32 s18, s18, 0xf00
	s_and_b32 s19, s19, 0xffffff80
	s_add_i32 s20, s18, s19
	ds_read2st64_b32 v[20:21], v7 offset1:1
	ds_read2st64_b32 v[12:13], v7 offset0:2 offset1:3
	ds_read2st64_b32 v[22:23], v7 offset0:4 offset1:5
	ds_read2st64_b32 v[14:15], v7 offset0:6 offset1:7
	s_and_b64 s[18:19], s[4:5], exec
	s_cselect_b32 s18, s20, s16
	v_or_b32_e32 v26, s18, v6
	v_ashrrev_i32_e32 v27, 31, v26
	v_lshlrev_b64 v[26:27], 11, v[26:27]
	s_waitcnt lgkmcnt(0)
	v_mov_b32_e32 v16, v20
	v_mov_b32_e32 v17, v12
	v_mov_b32_e32 v18, v22
	v_mov_b32_e32 v19, v14
	v_lshl_add_u64 v[26:27], v[24:25], 0, v[26:27]
	global_store_dwordx4 v[26:27], v[16:19], off nt
	v_mov_b32_e32 v12, v21
	v_mov_b32_e32 v14, v23
	v_add_u32_e32 v16, s16, v1
	v_lshlrev_b32_e32 v17, 1, v16
	v_ashrrev_i32_e32 v18, 4, v16
	v_and_b32_e32 v17, 0xf00, v17
	v_and_b32_e32 v18, 0xffffff80, v18
	v_add_u32_e32 v17, v17, v18
	v_or_b32_e32 v17, v17, v1
	v_cndmask_b32_e64 v16, v16, v17, s[4:5]
	v_ashrrev_i32_e32 v17, 31, v16
	v_lshlrev_b64 v[16:17], 11, v[16:17]
	v_lshl_add_u64 v[16:17], v[24:25], 0, v[16:17]
	global_store_dwordx4 v[16:17], v[12:15], off nt
	s_waitcnt lgkmcnt(0)
	s_barrier
	s_waitcnt vmcnt(8)
	v_add_u32_e32 v40, s29, v9
	ds_read2st64_b64 v[12:15], v40 offset1:1
	ds_read2st64_b64 v[16:19], v40 offset0:2 offset1:3
	ds_read2st64_b64 v[20:23], v40 offset0:4 offset1:5
	ds_read2st64_b64 v[24:27], v40 offset0:6 offset1:7
	ds_read2st64_b64 v[28:31], v40 offset0:8 offset1:9
	ds_read2st64_b64 v[32:35], v40 offset0:10 offset1:11
	ds_read2st64_b64 v[36:39], v40 offset0:12 offset1:13
	ds_read2st64_b64 v[40:43], v40 offset0:14 offset1:15
	s_waitcnt lgkmcnt(7)
	v_mul_f32_e32 v44, 0x42000000, v12
	v_mul_f32_e32 v14, 0x42000000, v14
	v_mov_b32_e32 v12, v3
	v_cvt_pk_fp8_f32 v12, v44, v14
	v_mul_f32_e32 v14, 0x42000000, v13
	v_mul_f32_e32 v15, 0x42000000, v15
	v_mov_b32_e32 v13, v3
	v_cvt_pk_fp8_f32 v13, v14, v15
	s_waitcnt lgkmcnt(6)
	v_mul_f32_e32 v16, 0x42000000, v16
	v_mul_f32_e32 v18, 0x42000000, v18
	v_mul_f32_e32 v14, 0x42000000, v17
	v_mul_f32_e32 v15, 0x42000000, v19
	v_cvt_pk_fp8_f32 v12, v16, v18 op_sel:[0,0,1]
	v_cvt_pk_fp8_f32 v13, v14, v15 op_sel:[0,0,1]
	s_waitcnt lgkmcnt(5)
	v_mul_f32_e32 v15, 0x42000000, v20
	v_mul_f32_e32 v16, 0x42000000, v22
	v_mov_b32_e32 v14, v3
	v_cvt_pk_fp8_f32 v14, v15, v16
	v_mul_f32_e32 v16, 0x42000000, v21
	v_mul_f32_e32 v19, 0x42000000, v23
	v_mov_b32_e32 v15, v3
	v_cvt_pk_fp8_f32 v15, v16, v19
	s_waitcnt lgkmcnt(4)
	v_mul_f32_e32 v17, 0x42000000, v24
	v_mul_f32_e32 v18, 0x42000000, v26
	v_cvt_pk_fp8_f32 v14, v17, v18 op_sel:[0,0,1]
	v_mul_f32_e32 v16, 0x42000000, v25
	v_mul_f32_e32 v17, 0x42000000, v27
	v_cvt_pk_fp8_f32 v15, v16, v17 op_sel:[0,0,1]
	s_waitcnt lgkmcnt(3)
	v_mul_f32_e32 v17, 0x42000000, v28
	v_mul_f32_e32 v18, 0x42000000, v30
	v_mov_b32_e32 v16, v3
	v_cvt_pk_fp8_f32 v16, v17, v18
	v_mul_f32_e32 v18, 0x42000000, v29
	v_mul_f32_e32 v21, 0x42000000, v31
	v_mov_b32_e32 v17, v3
	v_cvt_pk_fp8_f32 v17, v18, v21
	s_waitcnt lgkmcnt(2)
	v_mul_f32_e32 v19, 0x42000000, v32
	v_mul_f32_e32 v20, 0x42000000, v34
	v_cvt_pk_fp8_f32 v16, v19, v20 op_sel:[0,0,1]
	v_mul_f32_e32 v18, 0x42000000, v33
	v_mul_f32_e32 v19, 0x42000000, v35
	v_cvt_pk_fp8_f32 v17, v18, v19 op_sel:[0,0,1]
	s_waitcnt lgkmcnt(1)
	v_mul_f32_e32 v19, 0x42000000, v36
	v_mul_f32_e32 v20, 0x42000000, v38
	v_mov_b32_e32 v18, v3
	v_cvt_pk_fp8_f32 v18, v19, v20
	v_mul_f32_e32 v20, 0x42000000, v37
	v_mul_f32_e32 v23, 0x42000000, v39
	v_mov_b32_e32 v19, v3
	v_cvt_pk_fp8_f32 v19, v20, v23
	s_waitcnt lgkmcnt(0)
	v_mul_f32_e32 v21, 0x42000000, v40
	v_mul_f32_e32 v22, 0x42000000, v42
	v_cvt_pk_fp8_f32 v18, v21, v22 op_sel:[0,0,1]
	v_mul_f32_e32 v20, 0x42000000, v41
	v_mul_f32_e32 v21, 0x42000000, v43
	v_cvt_pk_fp8_f32 v19, v20, v21 op_sel:[0,0,1]
	ds_write2st64_b64 v11, v[12:13], v[14:15] offset1:1
	ds_write2st64_b64 v11, v[16:17], v[18:19] offset0:2 offset1:3
	s_waitcnt lgkmcnt(0)
	s_add_i32 s2, s33, s2
	s_min_i32 s2, s2, s0
	s_cmpk_gt_i32 s2, 0x3fff
	s_mov_b64 s[18:19], -1
	s_cbranch_scc0 .LBB0_816
	s_add_i32 s4, s2, 0xffffc000
	s_lshr_b32 s16, s4, 8
	s_lshl_b64 s[4:5], s[16:17], 24
	s_add_u32 s4, s12, s4
	s_addc_u32 s5, s13, s5
	s_mov_b64 s[18:19], 0

.LBB0_910:
	s_waitcnt lgkmcnt(0)
	s_barrier
	s_waitcnt vmcnt(8)
	ds_read2st64_b64 v[12:15], v9 offset1:1
	ds_read2st64_b64 v[16:19], v9 offset0:2 offset1:3
	ds_read2st64_b64 v[20:23], v9 offset0:4 offset1:5
	ds_read2st64_b64 v[24:27], v9 offset0:6 offset1:7
	ds_read2st64_b64 v[28:31], v9 offset0:8 offset1:9
	ds_read2st64_b64 v[32:35], v9 offset0:10 offset1:11
	ds_read2st64_b64 v[36:39], v9 offset0:12 offset1:13
	ds_read2st64_b64 v[40:43], v9 offset0:14 offset1:15
	s_waitcnt lgkmcnt(7)
	v_mul_f32_e32 v11, 0x42000000, v12
	v_mul_f32_e32 v14, 0x42000000, v14
	v_mov_b32_e32 v12, 0
	v_cvt_pk_fp8_f32 v12, v11, v14
	v_mul_f32_e32 v11, 0x42000000, v13
	v_mul_f32_e32 v14, 0x42000000, v15
	v_mov_b32_e32 v13, 0
	v_cvt_pk_fp8_f32 v13, v11, v14
	s_waitcnt lgkmcnt(6)
	v_mul_f32_e32 v11, 0x42000000, v17
	v_mul_f32_e32 v14, 0x42000000, v19
	v_mul_f32_e32 v16, 0x42000000, v16
	v_mul_f32_e32 v18, 0x42000000, v18
	v_cvt_pk_fp8_f32 v13, v11, v14 op_sel:[0,0,1]
	s_waitcnt lgkmcnt(5)
	v_mul_f32_e32 v11, 0x42000000, v20
	v_mul_f32_e32 v15, 0x42000000, v22
	v_mov_b32_e32 v14, 0
	v_cvt_pk_fp8_f32 v12, v16, v18 op_sel:[0,0,1]
	v_cvt_pk_fp8_f32 v14, v11, v15
	v_mul_f32_e32 v11, 0x42000000, v21
	v_mul_f32_e32 v18, 0x42000000, v23
	v_mov_b32_e32 v15, 0
	v_cvt_pk_fp8_f32 v15, v11, v18
	s_waitcnt lgkmcnt(4)
	v_mul_f32_e32 v16, 0x42000000, v24
	v_mul_f32_e32 v17, 0x42000000, v26
	v_cvt_pk_fp8_f32 v14, v16, v17 op_sel:[0,0,1]
	v_mul_f32_e32 v11, 0x42000000, v25
	v_mul_f32_e32 v16, 0x42000000, v27
	v_cvt_pk_fp8_f32 v15, v11, v16 op_sel:[0,0,1]
	s_waitcnt lgkmcnt(3)
	v_mul_f32_e32 v11, 0x42000000, v28
	v_mul_f32_e32 v17, 0x42000000, v30
	v_mov_b32_e32 v16, 0
	v_cvt_pk_fp8_f32 v16, v11, v17
	v_mul_f32_e32 v11, 0x42000000, v29
	v_mul_f32_e32 v20, 0x42000000, v31
	v_mov_b32_e32 v17, 0
	v_cvt_pk_fp8_f32 v17, v11, v20
	s_waitcnt lgkmcnt(2)
	v_mul_f32_e32 v18, 0x42000000, v32
	v_mul_f32_e32 v19, 0x42000000, v34
	v_cvt_pk_fp8_f32 v16, v18, v19 op_sel:[0,0,1]
	v_mul_f32_e32 v11, 0x42000000, v33
	v_mul_f32_e32 v18, 0x42000000, v35
	v_cvt_pk_fp8_f32 v17, v11, v18 op_sel:[0,0,1]
	s_waitcnt lgkmcnt(1)
	v_mul_f32_e32 v11, 0x42000000, v36
	v_mul_f32_e32 v19, 0x42000000, v38
	v_mov_b32_e32 v18, 0
	v_cvt_pk_fp8_f32 v18, v11, v19
	v_mul_f32_e32 v11, 0x42000000, v37
	v_mul_f32_e32 v22, 0x42000000, v39
	v_mov_b32_e32 v19, 0
	v_cvt_pk_fp8_f32 v19, v11, v22
	s_waitcnt lgkmcnt(0)
	v_mul_f32_e32 v20, 0x42000000, v40
	v_mul_f32_e32 v21, 0x42000000, v42
	v_cvt_pk_fp8_f32 v18, v20, v21 op_sel:[0,0,1]
	v_mul_f32_e32 v11, 0x42000000, v41
	v_mul_f32_e32 v20, 0x42000000, v43
	v_cvt_pk_fp8_f32 v19, v11, v20 op_sel:[0,0,1]
	ds_write2st64_b64 v10, v[12:13], v[14:15] offset1:1
	ds_write2st64_b64 v10, v[16:17], v[18:19] offset0:2 offset1:3
	s_waitcnt lgkmcnt(0)
	s_add_i32 s35, s33, s2
	s_min_i32 s18, s35, s0
	s_cmpk_gt_i32 s18, 0x3fff
	s_mov_b64 s[16:17], -1
	s_cbranch_scc0 .LBB0_912
	s_add_i32 s4, s18, 0xffffc000
	s_lshr_b32 s12, s4, 8
	s_lshl_b64 s[4:5], s[12:13], 24
	s_add_u32 s4, s10, s4
	s_addc_u32 s5, s11, s5
	s_mov_b64 s[16:17], 0

.LBB0_919:
	s_lshl_b32 s18, s36, 3
	s_and_b32 s12, s18, s12
	s_lshl_b32 s18, s36, 7
	s_and_b32 s18, s18, 0x780
	s_add_u32 s16, s16, s18
	s_addc_u32 s17, s17, 0
	v_lshl_add_u64 v[24:25], s[16:17], 0, v[4:5]
	s_lshl_b32 s16, s12, 1
	s_ashr_i32 s17, s12, 4
	s_and_b32 s16, s16, 0xf00
	s_and_b32 s17, s17, 0xffffff80
	s_add_i32 s18, s16, s17
	ds_read2st64_b32 v[20:21], v6 offset1:1
	ds_read2st64_b32 v[12:13], v6 offset0:2 offset1:3
	ds_read2st64_b32 v[22:23], v6 offset0:4 offset1:5
	ds_read2st64_b32 v[14:15], v6 offset0:6 offset1:7
	s_and_b64 s[16:17], s[4:5], exec
	s_cselect_b32 s16, s18, s12
	v_or_b32_e32 v26, s16, v186
	v_ashrrev_i32_e32 v27, 31, v26
	v_lshlrev_b64 v[26:27], 11, v[26:27]
	s_waitcnt lgkmcnt(0)
	v_mov_b32_e32 v16, v20
	v_mov_b32_e32 v17, v12
	v_mov_b32_e32 v18, v22
	v_mov_b32_e32 v19, v14
	v_lshl_add_u64 v[26:27], v[24:25], 0, v[26:27]
	v_add_u32_e32 v11, s12, v1
	global_store_dwordx4 v[26:27], v[16:19], off nt
	v_mov_b32_e32 v12, v21
	v_mov_b32_e32 v14, v23
	v_lshlrev_b32_e32 v16, 1, v11
	v_ashrrev_i32_e32 v17, 4, v11
	v_and_b32_e32 v16, 0xf00, v16
	v_and_b32_e32 v17, 0xffffff80, v17
	v_add_u32_e32 v16, v16, v17
	v_or_b32_e32 v16, v16, v1
	v_cndmask_b32_e64 v16, v11, v16, s[4:5]
	v_ashrrev_i32_e32 v17, 31, v16
	v_lshlrev_b64 v[16:17], 11, v[16:17]
	v_lshl_add_u64 v[16:17], v[24:25], 0, v[16:17]
	global_store_dwordx4 v[16:17], v[12:15], off nt
	s_waitcnt lgkmcnt(0)
	s_barrier
	s_waitcnt vmcnt(8)
	v_add_u32_e32 v11, s27, v8
	ds_read2st64_b64 v[12:15], v11 offset1:1
	ds_read2st64_b64 v[16:19], v11 offset0:2 offset1:3
	ds_read2st64_b64 v[20:23], v11 offset0:4 offset1:5
	ds_read2st64_b64 v[24:27], v11 offset0:6 offset1:7
	ds_read2st64_b64 v[28:31], v11 offset0:8 offset1:9
	ds_read2st64_b64 v[32:35], v11 offset0:10 offset1:11
	ds_read2st64_b64 v[36:39], v11 offset0:12 offset1:13
	ds_read2st64_b64 v[40:43], v11 offset0:14 offset1:15
	s_waitcnt lgkmcnt(7)
	v_mul_f32_e32 v11, 0x42000000, v12
	v_mul_f32_e32 v14, 0x42000000, v14
	v_mov_b32_e32 v12, v3
	v_cvt_pk_fp8_f32 v12, v11, v14
	v_mul_f32_e32 v11, 0x42000000, v13
	v_mul_f32_e32 v14, 0x42000000, v15
	v_mov_b32_e32 v13, v3
	v_cvt_pk_fp8_f32 v13, v11, v14
	s_waitcnt lgkmcnt(6)
	v_mul_f32_e32 v11, 0x42000000, v17
	v_mul_f32_e32 v14, 0x42000000, v19
	v_mul_f32_e32 v16, 0x42000000, v16
	v_mul_f32_e32 v18, 0x42000000, v18
	v_cvt_pk_fp8_f32 v13, v11, v14 op_sel:[0,0,1]
	s_waitcnt lgkmcnt(5)
	v_mul_f32_e32 v11, 0x42000000, v20
	v_mul_f32_e32 v15, 0x42000000, v22
	v_mov_b32_e32 v14, v3
	v_cvt_pk_fp8_f32 v12, v16, v18 op_sel:[0,0,1]
	v_cvt_pk_fp8_f32 v14, v11, v15
	v_mul_f32_e32 v11, 0x42000000, v21
	v_mul_f32_e32 v18, 0x42000000, v23
	v_mov_b32_e32 v15, v3
	v_cvt_pk_fp8_f32 v15, v11, v18
	s_waitcnt lgkmcnt(4)
	v_mul_f32_e32 v16, 0x42000000, v24
	v_mul_f32_e32 v17, 0x42000000, v26
	v_cvt_pk_fp8_f32 v14, v16, v17 op_sel:[0,0,1]
	v_mul_f32_e32 v11, 0x42000000, v25
	v_mul_f32_e32 v16, 0x42000000, v27
	v_cvt_pk_fp8_f32 v15, v11, v16 op_sel:[0,0,1]
	s_waitcnt lgkmcnt(3)
	v_mul_f32_e32 v11, 0x42000000, v28
	v_mul_f32_e32 v17, 0x42000000, v30
	v_mov_b32_e32 v16, v3
	v_cvt_pk_fp8_f32 v16, v11, v17
	v_mul_f32_e32 v11, 0x42000000, v29
	v_mul_f32_e32 v20, 0x42000000, v31
	v_mov_b32_e32 v17, v3
	v_cvt_pk_fp8_f32 v17, v11, v20
	s_waitcnt lgkmcnt(2)
	v_mul_f32_e32 v18, 0x42000000, v32
	v_mul_f32_e32 v19, 0x42000000, v34
	v_cvt_pk_fp8_f32 v16, v18, v19 op_sel:[0,0,1]
	v_mul_f32_e32 v11, 0x42000000, v33
	v_mul_f32_e32 v18, 0x42000000, v35
	v_cvt_pk_fp8_f32 v17, v11, v18 op_sel:[0,0,1]
	s_waitcnt lgkmcnt(1)
	v_mul_f32_e32 v11, 0x42000000, v36
	v_mul_f32_e32 v19, 0x42000000, v38
	v_mov_b32_e32 v18, v3
	v_cvt_pk_fp8_f32 v18, v11, v19
	v_mul_f32_e32 v11, 0x42000000, v37
	v_mul_f32_e32 v22, 0x42000000, v39
	v_mov_b32_e32 v19, v3
	v_cvt_pk_fp8_f32 v19, v11, v22
	s_waitcnt lgkmcnt(0)
	v_mul_f32_e32 v20, 0x42000000, v40
	v_mul_f32_e32 v21, 0x42000000, v42
	v_cvt_pk_fp8_f32 v18, v20, v21 op_sel:[0,0,1]
	v_mul_f32_e32 v11, 0x42000000, v41
	v_mul_f32_e32 v20, 0x42000000, v43
	v_cvt_pk_fp8_f32 v19, v11, v20 op_sel:[0,0,1]
	ds_write2st64_b64 v10, v[12:13], v[14:15] offset1:1
	ds_write2st64_b64 v10, v[16:17], v[18:19] offset0:2 offset1:3
	s_waitcnt lgkmcnt(0)
	s_add_i32 s2, s30, s2
	s_min_i32 s2, s2, s0
	s_cmpk_gt_i32 s2, 0x3fff
	s_mov_b64 s[16:17], -1
	s_cbranch_scc0 .LBB0_921
	s_add_i32 s4, s2, 0xffffc000
	s_lshr_b32 s12, s4, 8
	s_lshl_b64 s[4:5], s[12:13], 24
	s_add_u32 s4, s10, s4
	s_addc_u32 s5, s11, s5
	s_mov_b64 s[16:17], 0
